# P1 sample tiles: next tile's first two LDS-DMA rounds issued right after the reduction barrier of the current tile (overlap with its epilogue); on top of v63
# speedup vs baseline: 1.0055x; 1.0014x over previous
.LBB0_125:
	s_mul_hi_i32 s28, s61, 0x2aaaaaab
	s_lshr_b32 s29, s28, 31
	s_ashr_i32 s28, s28, 3
	s_add_i32 s31, s28, s29
	s_mul_i32 s28, s31, 0xffffffd0
	s_add_i32 s63, s61, s28
	s_mul_i32 s28, s31, 0xfffff400
	s_add_i32 s30, s27, s28
	s_and_b32 s28, s30, 0xffffff00
	s_and_b32 s29, s54, 0x60
	s_or_b32 s28, s28, s29
	s_ashr_i32 s29, s28, 31
	s_lshl_b64 s[34:35], s[28:29], 11
	s_add_u32 s34, s3, s34
	s_addc_u32 s35, s39, s35
	s_bitset1_b32 s28, 7
	s_ashr_i32 s29, s28, 31
	v_mov_b32_e32 v37, v228
	s_lshl_b64 s[28:29], s[28:29], 11
	s_add_u32 s36, s3, s28
	v_and_b32_e32 v122, 31, v37
	v_ashrrev_i32_e32 v123, 5, v37
	s_addc_u32 s37, s39, s29
	s_lshl_b32 s28, s31, 5
	s_ashr_i32 s29, s28, 31
	s_lshl_b64 s[64:65], s[28:29], 11
	s_add_u32 s64, s58, s64
	s_addc_u32 s65, s59, s65
	s_mov_b32 s101, m0
	s_mul_i32 s100, s2, 0x180
	v_lshrrev_b32_e32 v14, 2, v37
	v_bfe_u32 v15, v37, 4, 2
	v_lshlrev_b32_e32 v14, 11, v14
	v_xor_b32_e32 v15, v15, v37
	v_bfe_u32 v16, v122, 2, 2
	v_and_b32_e32 v15, 3, v15
	v_xor_b32_e32 v16, v16, v123
	v_lshl_or_b32 v14, v15, 4, v14
	v_lshlrev_b32_e32 v16, 4, v16
	v_lshl_or_b32 v15, v122, 6, v16
	v_add_u32_e32 v15, s100, v15
	v_xor_b32_e32 v16, 32, v15
	s_cmp_lg_u32 s61, s83
	s_cbranch_scc1 .Lp1_skip01
	s_add_u32 s98, s34, s0
	s_addc_u32 s99, s35, 0
	s_add_i32 m0, s100, 0x0
	s_nop 0
	global_load_lds_dwordx4 v14, s[98:99]
	s_add_u32 s98, s34, s0
	s_addc_u32 s99, s35, 0
	s_add_u32 s98, s98, 0x8000
	s_addc_u32 s99, s99, 0
	s_add_i32 m0, s100, 0x400
	s_nop 0
	global_load_lds_dwordx4 v14, s[98:99]
	s_add_u32 s98, s36, s0
	s_addc_u32 s99, s37, 0
	s_add_i32 m0, s100, 0x800
	s_nop 0
	global_load_lds_dwordx4 v14, s[98:99]
	s_add_u32 s98, s36, s0
	s_addc_u32 s99, s37, 0
	s_add_u32 s98, s98, 0x8000
	s_addc_u32 s99, s99, 0
	s_add_i32 m0, s100, 0xc00
	s_nop 0
	global_load_lds_dwordx4 v14, s[98:99]
	s_add_u32 s98, s64, s0
	s_addc_u32 s99, s65, 0
	s_add_u32 s98, s98, 0x2000000
	s_addc_u32 s99, s99, 0
	s_add_i32 m0, s100, 0x1000
	s_nop 0
	global_load_lds_dwordx4 v14, s[98:99]
	s_add_u32 s98, s64, s0
	s_addc_u32 s99, s65, 0
	s_add_u32 s98, s98, 0x2008000
	s_addc_u32 s99, s99, 0
	s_add_i32 m0, s100, 0x1400
	s_nop 0
	global_load_lds_dwordx4 v14, s[98:99]
	s_add_u32 s98, s34, s0
	s_addc_u32 s99, s35, 0
	s_add_u32 s98, s98, 0x40
	s_addc_u32 s99, s99, 0
	s_add_i32 m0, s100, 0x1800
	s_nop 0
	global_load_lds_dwordx4 v14, s[98:99]
	s_add_u32 s98, s34, s0
	s_addc_u32 s99, s35, 0
	s_add_u32 s98, s98, 0x8040
	s_addc_u32 s99, s99, 0
	s_add_i32 m0, s100, 0x1c00
	s_nop 0
	global_load_lds_dwordx4 v14, s[98:99]
	s_add_u32 s98, s36, s0
	s_addc_u32 s99, s37, 0
	s_add_u32 s98, s98, 0x40
	s_addc_u32 s99, s99, 0
	s_add_i32 m0, s100, 0x2000
	s_nop 0
	global_load_lds_dwordx4 v14, s[98:99]
	s_add_u32 s98, s36, s0
	s_addc_u32 s99, s37, 0
	s_add_u32 s98, s98, 0x8040
	s_addc_u32 s99, s99, 0
	s_add_i32 m0, s100, 0x2400
	s_nop 0
	global_load_lds_dwordx4 v14, s[98:99]
	s_add_u32 s98, s64, s0
	s_addc_u32 s99, s65, 0
	s_add_u32 s98, s98, 0x2000040
	s_addc_u32 s99, s99, 0
	s_add_i32 m0, s100, 0x2800
	s_nop 0
	global_load_lds_dwordx4 v14, s[98:99]
	s_add_u32 s98, s64, s0
	s_addc_u32 s99, s65, 0
	s_add_u32 s98, s98, 0x2008040
	s_addc_u32 s99, s99, 0
	s_add_i32 m0, s100, 0x2c00
	s_nop 0
	global_load_lds_dwordx4 v14, s[98:99]
.Lp1_skip01:
	s_waitcnt vmcnt(6)
	ds_read_b128 v[2:5], v15
	ds_read_b128 v[6:9], v15 offset:2048
	ds_read_b128 v[10:13], v15 offset:4096
	ds_read_b128 v[38:41], v16
	ds_read_b128 v[42:45], v16 offset:2048
	ds_read_b128 v[46:49], v16 offset:4096
	s_waitcnt lgkmcnt(0)
	s_add_u32 s98, s34, s0
	s_addc_u32 s99, s35, 0
	s_add_u32 s98, s98, 0x80
	s_addc_u32 s99, s99, 0
	s_add_i32 m0, s100, 0x0
	s_nop 0
	global_load_lds_dwordx4 v14, s[98:99]
	s_add_u32 s98, s34, s0
	s_addc_u32 s99, s35, 0
	s_add_u32 s98, s98, 0x8080
	s_addc_u32 s99, s99, 0
	s_add_i32 m0, s100, 0x400
	s_nop 0
	global_load_lds_dwordx4 v14, s[98:99]
	s_add_u32 s98, s36, s0
	s_addc_u32 s99, s37, 0
	s_add_u32 s98, s98, 0x80
	s_addc_u32 s99, s99, 0
	s_add_i32 m0, s100, 0x800
	s_nop 0
	global_load_lds_dwordx4 v14, s[98:99]
	s_add_u32 s98, s36, s0
	s_addc_u32 s99, s37, 0
	s_add_u32 s98, s98, 0x8080
	s_addc_u32 s99, s99, 0
	s_add_i32 m0, s100, 0xc00
	s_nop 0
	global_load_lds_dwordx4 v14, s[98:99]
	s_add_u32 s98, s64, s0
	s_addc_u32 s99, s65, 0
	s_add_u32 s98, s98, 0x2000080
	s_addc_u32 s99, s99, 0
	s_add_i32 m0, s100, 0x1000
	s_nop 0
	global_load_lds_dwordx4 v14, s[98:99]
	s_add_u32 s98, s64, s0
	s_addc_u32 s99, s65, 0
	s_add_u32 s98, s98, 0x2008080
	s_addc_u32 s99, s99, 0
	s_add_i32 m0, s100, 0x1400
	s_nop 0
	global_load_lds_dwordx4 v14, s[98:99]
	s_waitcnt vmcnt(6)
	ds_read_b128 v[54:57], v15 offset:6144
	ds_read_b128 v[62:65], v15 offset:8192
	ds_read_b128 v[50:53], v15 offset:10240
	ds_read_b128 v[58:61], v16 offset:6144
	ds_read_b128 v[66:69], v16 offset:8192
	ds_read_b128 v[70:73], v16 offset:10240
	s_waitcnt lgkmcnt(0)
	s_add_u32 s98, s34, s0
	s_addc_u32 s99, s35, 0
	s_add_u32 s98, s98, 0xc0
	s_addc_u32 s99, s99, 0
	s_add_i32 m0, s100, 0x1800
	s_nop 0
	global_load_lds_dwordx4 v14, s[98:99]
	s_add_u32 s98, s34, s0
	s_addc_u32 s99, s35, 0
	s_add_u32 s98, s98, 0x80c0
	s_addc_u32 s99, s99, 0
	s_add_i32 m0, s100, 0x1c00
	s_nop 0
	global_load_lds_dwordx4 v14, s[98:99]
	s_add_u32 s98, s36, s0
	s_addc_u32 s99, s37, 0
	s_add_u32 s98, s98, 0xc0
	s_addc_u32 s99, s99, 0
	s_add_i32 m0, s100, 0x2000
	s_nop 0
	global_load_lds_dwordx4 v14, s[98:99]
	s_add_u32 s98, s36, s0
	s_addc_u32 s99, s37, 0
	s_add_u32 s98, s98, 0x80c0
	s_addc_u32 s99, s99, 0
	s_add_i32 m0, s100, 0x2400
	s_nop 0
	global_load_lds_dwordx4 v14, s[98:99]
	s_add_u32 s98, s64, s0
	s_addc_u32 s99, s65, 0
	s_add_u32 s98, s98, 0x20000c0
	s_addc_u32 s99, s99, 0
	s_add_i32 m0, s100, 0x2800
	s_nop 0
	global_load_lds_dwordx4 v14, s[98:99]
	s_add_u32 s98, s64, s0
	s_addc_u32 s99, s65, 0
	s_add_u32 s98, s98, 0x20080c0
	s_addc_u32 s99, s99, 0
	s_add_i32 m0, s100, 0x2c00
	s_nop 0
	global_load_lds_dwordx4 v14, s[98:99]
	s_waitcnt vmcnt(6)
	ds_read_b128 v[78:81], v15
	ds_read_b128 v[86:89], v15 offset:2048
	ds_read_b128 v[74:77], v15 offset:4096
	ds_read_b128 v[82:85], v16
	ds_read_b128 v[90:93], v16 offset:2048
	ds_read_b128 v[94:97], v16 offset:4096
	s_waitcnt vmcnt(0)
	ds_read_b128 v[102:105], v15 offset:6144
	ds_read_b128 v[110:113], v15 offset:8192
	ds_read_b128 v[98:101], v15 offset:10240
	ds_read_b128 v[106:109], v16 offset:6144
	ds_read_b128 v[114:117], v16 offset:8192
	ds_read_b128 v[118:121], v16 offset:10240
	s_mov_b32 m0, s101
	s_waitcnt lgkmcnt(0)
	v_mfma_f32_32x32x16_bf16 v[18:33], v[2:5], v[10:13], 0
	v_or_b32_e32 v34, s2, v122
	v_mul_lo_u32 v34, v34, s57
	s_ashr_i32 s64, s63, 3
	v_mfma_f32_32x32x16_bf16 v[2:17], v[6:9], v[10:13], 0
	v_mfma_f32_32x32x16_bf16 v[18:33], v[38:41], v[46:49], v[18:33]
	v_lshlrev_b32_e32 v38, 4, v123
	v_add3_u32 v34, 0, v34, v38
	v_mfma_f32_32x32x16_bf16 v[2:17], v[42:45], v[46:49], v[2:17]
	v_mfma_f32_32x32x16_bf16 v[18:33], v[54:57], v[50:53], v[18:33]
	v_mfma_f32_32x32x16_bf16 v[2:17], v[62:65], v[50:53], v[2:17]
	v_mfma_f32_32x32x16_bf16 v[18:33], v[58:61], v[70:73], v[18:33]
	v_mfma_f32_32x32x16_bf16 v[2:17], v[66:69], v[70:73], v[2:17]
	v_mfma_f32_32x32x16_bf16 v[18:33], v[78:81], v[74:77], v[18:33]
	v_mfma_f32_32x32x16_bf16 v[2:17], v[86:89], v[74:77], v[2:17]
	v_mfma_f32_32x32x16_bf16 v[18:33], v[82:85], v[94:97], v[18:33]
	v_mfma_f32_32x32x16_bf16 v[2:17], v[90:93], v[94:97], v[2:17]
	v_mfma_f32_32x32x16_bf16 v[18:33], v[102:105], v[98:101], v[18:33]
	v_mfma_f32_32x32x16_bf16 v[2:17], v[110:113], v[98:101], v[2:17]
	v_mfma_f32_32x32x16_bf16 v[18:33], v[106:109], v[118:121], v[18:33]
	v_mfma_f32_32x32x16_bf16 v[2:17], v[114:117], v[118:121], v[2:17]
	s_nop 10
	s_barrier
	ds_write_b128 v34, v[18:21]
	ds_write_b128 v34, v[2:5] offset:128
	ds_write_b128 v34, v[22:25] offset:32
	ds_write_b128 v34, v[6:9] offset:160
	ds_write_b128 v34, v[26:29] offset:64
	ds_write_b128 v34, v[10:13] offset:192
	ds_write_b128 v34, v[30:33] offset:96
	ds_write_b128 v34, v[14:17] offset:224
	v_add_u32_e32 v2, s26, v37
	v_ashrrev_i32_e32 v13, 4, v2
	v_lshlrev_b32_e32 v2, 2, v37
	v_and_b32_e32 v20, 60, v2
	v_lshlrev_b32_e32 v12, 2, v20
	v_mul_lo_u32 v2, v13, s57
	v_add3_u32 v21, 0, v12, v2
	s_waitcnt lgkmcnt(0)
	s_barrier
	ds_read_b128 v[2:5], v21
	ds_read_b128 v[6:9], v21 offset:8704
	ds_read_b128 v[14:17], v21 offset:17408
	s_waitcnt lgkmcnt(2)
	v_pk_add_f32 v[4:5], v[4:5], 0 op_sel_hi:[1,0]
	v_pk_add_f32 v[10:11], v[2:3], 0 op_sel_hi:[1,0]
	s_waitcnt lgkmcnt(1)
	v_pk_add_f32 v[8:9], v[4:5], v[8:9]
	ds_read_b128 v[2:5], v21 offset:26112
	v_pk_add_f32 v[10:11], v[10:11], v[6:7]
	s_waitcnt lgkmcnt(1)
	v_pk_add_f32 v[16:17], v[8:9], v[16:17]
	ds_read_b128 v[6:9], v21 offset:34816
	v_pk_add_f32 v[10:11], v[10:11], v[14:15]
	s_waitcnt lgkmcnt(1)
	v_pk_add_f32 v[14:15], v[16:17], v[4:5]
	v_pk_add_f32 v[16:17], v[10:11], v[2:3]
	ds_read_b128 v[2:5], v21 offset:43520
	s_waitcnt lgkmcnt(1)
	v_pk_add_f32 v[18:19], v[14:15], v[8:9]
	ds_read_b128 v[8:11], v21 offset:52224
	v_pk_add_f32 v[6:7], v[16:17], v[6:7]
	ds_read_b128 v[14:17], v21 offset:60928
	s_waitcnt lgkmcnt(2)
	v_pk_add_f32 v[2:3], v[6:7], v[2:3]
	v_add_u32_e32 v6, s28, v13
	v_pk_add_f32 v[4:5], v[18:19], v[4:5]
	v_ashrrev_i32_e32 v7, 31, v6
	s_waitcnt lgkmcnt(1)
	v_pk_add_f32 v[4:5], v[4:5], v[10:11]
	v_pk_add_f32 v[2:3], v[2:3], v[8:9]
	v_lshlrev_b64 v[10:11], 9, v[6:7]
	s_and_b32 s28, s30, 0x1c0
	s_waitcnt lgkmcnt(0)
	v_pk_add_f32 v[4:5], v[4:5], v[16:17]
	v_pk_add_f32 v[2:3], v[2:3], v[14:15]
	v_or3_b32 v10, v10, s28, v20
	s_cmp_gt_i32 s64, 1
	s_mov_b64 s[28:29], -1
	s_barrier
	v_readlane_b32 s66, v252, 2
	s_add_i32 s66, s61, s66
	s_cmpk_gt_i32 s66, 0x2ff
	s_cbranch_scc1 .Lp1_nopf
	s_add_i32 s67, s27, s33
	s_add_i32 s68, s54, s55
	s_mul_hi_i32 s69, s66, 0x2aaaaaab
	s_lshr_b32 s79, s69, 31
	s_ashr_i32 s69, s69, 3
	s_add_i32 s78, s69, s79
	s_mul_i32 s69, s78, 0xfffff400
	s_add_i32 s69, s67, s69
	s_and_b32 s70, s69, 0xffffff00
	s_and_b32 s79, s68, 0x60
	s_or_b32 s70, s70, s79
	s_ashr_i32 s71, s70, 31
	s_lshl_b64 s[72:73], s[70:71], 11
	s_add_u32 s72, s3, s72
	s_addc_u32 s73, s39, s73
	s_bitset1_b32 s70, 7
	s_ashr_i32 s71, s70, 31
	s_lshl_b64 s[74:75], s[70:71], 11
	s_add_u32 s74, s3, s74
	s_addc_u32 s75, s39, s75
	s_lshl_b32 s70, s78, 5
	s_ashr_i32 s71, s70, 31
	s_lshl_b64 s[76:77], s[70:71], 11
	s_add_u32 s76, s58, s76
	s_addc_u32 s77, s59, s77
	v_lshrrev_b32_e32 v39, 2, v37
	v_bfe_u32 v40, v37, 4, 2
	v_lshlrev_b32_e32 v39, 11, v39
	v_xor_b32_e32 v40, v40, v37
	v_and_b32_e32 v40, 3, v40
	v_lshl_or_b32 v39, v40, 4, v39
	s_mov_b32 s101, m0
	s_add_u32 s98, s72, s0
	s_addc_u32 s99, s73, 0
	s_add_i32 m0, s100, 0x0
	s_nop 0
	global_load_lds_dwordx4 v39, s[98:99]
	s_add_u32 s98, s72, s0
	s_addc_u32 s99, s73, 0
	s_add_u32 s98, s98, 0x8000
	s_addc_u32 s99, s99, 0
	s_add_i32 m0, s100, 0x400
	s_nop 0
	global_load_lds_dwordx4 v39, s[98:99]
	s_add_u32 s98, s74, s0
	s_addc_u32 s99, s75, 0
	s_add_i32 m0, s100, 0x800
	s_nop 0
	global_load_lds_dwordx4 v39, s[98:99]
	s_add_u32 s98, s74, s0
	s_addc_u32 s99, s75, 0
	s_add_u32 s98, s98, 0x8000
	s_addc_u32 s99, s99, 0
	s_add_i32 m0, s100, 0xc00
	s_nop 0
	global_load_lds_dwordx4 v39, s[98:99]
	s_add_u32 s98, s76, s0
	s_addc_u32 s99, s77, 0
	s_add_u32 s98, s98, 0x2000000
	s_addc_u32 s99, s99, 0
	s_add_i32 m0, s100, 0x1000
	s_nop 0
	global_load_lds_dwordx4 v39, s[98:99]
	s_add_u32 s98, s76, s0
	s_addc_u32 s99, s77, 0
	s_add_u32 s98, s98, 0x2008000
	s_addc_u32 s99, s99, 0
	s_add_i32 m0, s100, 0x1400
	s_nop 0
	global_load_lds_dwordx4 v39, s[98:99]
	s_add_u32 s98, s72, s0
	s_addc_u32 s99, s73, 0
	s_add_u32 s98, s98, 0x40
	s_addc_u32 s99, s99, 0
	s_add_i32 m0, s100, 0x1800
	s_nop 0
	global_load_lds_dwordx4 v39, s[98:99]
	s_add_u32 s98, s72, s0
	s_addc_u32 s99, s73, 0
	s_add_u32 s98, s98, 0x8040
	s_addc_u32 s99, s99, 0
	s_add_i32 m0, s100, 0x1c00
	s_nop 0
	global_load_lds_dwordx4 v39, s[98:99]
	s_add_u32 s98, s74, s0
	s_addc_u32 s99, s75, 0
	s_add_u32 s98, s98, 0x40
	s_addc_u32 s99, s99, 0
	s_add_i32 m0, s100, 0x2000
	s_nop 0
	global_load_lds_dwordx4 v39, s[98:99]
	s_add_u32 s98, s74, s0
	s_addc_u32 s99, s75, 0
	s_add_u32 s98, s98, 0x8040
	s_addc_u32 s99, s99, 0
	s_add_i32 m0, s100, 0x2400
	s_nop 0
	global_load_lds_dwordx4 v39, s[98:99]
	s_add_u32 s98, s76, s0
	s_addc_u32 s99, s77, 0
	s_add_u32 s98, s98, 0x2000040
	s_addc_u32 s99, s99, 0
	s_add_i32 m0, s100, 0x2800
	s_nop 0
	global_load_lds_dwordx4 v39, s[98:99]
	s_add_u32 s98, s76, s0
	s_addc_u32 s99, s77, 0
	s_add_u32 s98, s98, 0x2008040
	s_addc_u32 s99, s99, 0
	s_add_i32 m0, s100, 0x2c00
	s_nop 0
	global_load_lds_dwordx4 v39, s[98:99]
	s_mov_b32 m0, s101
.Lp1_nopf:
	s_cmp_gt_i32 s64, 1
	s_cbranch_scc0 .LBB0_138
	s_mov_b64 s[36:37], -1
	s_mov_b64 s[28:29], 0
	s_cmp_lt_i32 s64, 4
	s_mov_b64 s[30:31], 0
	s_mov_b64 s[34:35], 0
	s_cbranch_scc1 .LBB0_131
	s_cmp_lg_u32 s64, 4
	s_mov_b64 s[30:31], -1
	s_cselect_b64 s[34:35], -1, 0
	s_cbranch_execz .LBB0_132
